# FoX: decay-bias loads issued at the tile-loop top, ahead of the next tile's LDS-DMA, so the softmax wait no longer drains the DMA
# speedup vs baseline: 1.0001x; 1.0001x over previous
.LBB0_61:
	s_lshl_b32 s84, s23, 6
	v_lshl_add_u64 v[158:159], s[84:85], 2, v[146:147]
	global_load_dwordx4 v[224:227], v[158:159], off
	global_load_dwordx4 v[228:231], v[158:159], off offset:64
	global_load_dwordx4 v[232:235], v[158:159], off offset:128
	global_load_dwordx4 v[236:239], v[158:159], off offset:192
	s_cmp_lg_u64 s[16:17], 0
	s_cselect_b64 s[14:15], -1, 0
	s_cmp_eq_u64 s[16:17], 0
	s_cselect_b64 s[12:13], -1, 0
	s_mov_b64 s[10:11], 0
	s_and_b64 vcc, exec, s[12:13]
	s_cbranch_vccnz .LBB0_63
	s_add_u32 s4, s16, -1
	s_ff1_i32_b64 s22, s[16:17]
	s_addc_u32 s5, s17, -1
	s_and_b64 s[10:11], s[4:5], s[16:17]
	s_lshl_b32 s4, s22, 7
	s_add_u32 s4, s19, s4
	s_addc_u32 s5, s20, 0
	s_lshl_b32 s16, s21, 14
	s_xor_b32 s16, s16, 0x4000
	s_mul_i32 s84, s22, 0x60000
	v_add_u32_e32 v70, s16, v136
	v_lshl_add_u64 v[64:65], v[144:145], 0, s[84:85]
	v_readfirstlane_b32 s24, v70
	s_or_b32 s17, s16, 0x2000
	v_lshl_add_u64 v[66:67], v[132:133], 1, v[64:65]
	s_mov_b32 m0, s24
	v_lshl_add_u64 v[68:69], v[134:135], 1, s[4:5]
	global_load_lds_dwordx4 v[66:67], off
	v_add_u32_e32 v66, s17, v136
	v_lshl_add_u64 v[68:69], v[68:69], 0, v[152:153]
	v_readfirstlane_b32 s24, v66
	s_mov_b32 m0, s24
	v_lshl_add_u64 v[66:67], v[140:141], 1, s[4:5]
	global_load_lds_dwordx4 v[68:69], off
	v_add_u32_e32 v68, s16, v142
	v_lshl_add_u64 v[64:65], v[138:139], 1, v[64:65]
	v_readfirstlane_b32 s4, v68
	s_mov_b32 m0, s4
	v_mov_b32_e32 v149, v153
	global_load_lds_dwordx4 v[64:65], off
	v_add_u32_e32 v64, s17, v142
	v_lshl_add_u64 v[66:67], v[66:67], 0, v[148:149]
	v_readfirstlane_b32 s4, v64
	s_mov_b32 m0, s4
	s_nop 0
	global_load_lds_dwordx4 v[66:67], off

.Lfoxf_fast:
	s_lshl_b32 s4, s21, 14
	v_or_b32_e32 v193, s4, v178
	v_add_u32_e32 v248, v193, v176
	v_add_u32_e32 v249, v193, v177
	v_add_u32_e32 v191, v175, v176
	v_add_u32_e32 v192, v175, v177
	v_add_u32_e32 v187, v193, v181
	v_add_u32_e32 v188, v193, v182
	v_add_u32_e32 v189, v193, v183
	v_add_u32_e32 v190, v193, v184
	ds_read_b128 v[64:67], v248
	ds_read_b128 v[68:71], v248 offset:2048
	ds_read_b128 v[72:75], v249
	ds_read_b128 v[76:79], v249 offset:2048
	ds_read_b128 v[96:99], v191 offset:32768
	ds_read_b128 v[100:103], v192 offset:32768
	ds_read_b128 v[104:107], v191 offset:34816
	ds_read_b128 v[108:111], v192 offset:34816
	ds_read_b64 v[80:81], v187 offset:8192
	ds_read_b64 v[82:83], v188 offset:8192
	ds_read_b64 v[84:85], v187 offset:10240
	ds_read_b64 v[86:87], v188 offset:10240
	ds_read_b64 v[88:89], v187 offset:12288
	ds_read_b64 v[90:91], v188 offset:12288
	ds_read_b64 v[92:93], v187 offset:14336
	ds_read_b64 v[94:95], v188 offset:14336
	s_waitcnt lgkmcnt(8)
	v_mfma_f32_16x16x32_bf16 v[112:115], v[64:67], v[96:99], 0
	v_mfma_f32_16x16x32_bf16 v[116:119], v[68:71], v[96:99], 0
	v_mfma_f32_16x16x32_bf16 v[120:123], v[64:67], v[104:107], 0
	v_mfma_f32_16x16x32_bf16 v[124:127], v[68:71], v[104:107], 0
	v_mfma_f32_16x16x32_bf16 v[112:115], v[72:75], v[100:103], v[112:115]
	v_mfma_f32_16x16x32_bf16 v[116:119], v[76:79], v[100:103], v[116:119]
	v_mfma_f32_16x16x32_bf16 v[120:123], v[72:75], v[108:111], v[120:123]
	v_mfma_f32_16x16x32_bf16 v[124:127], v[76:79], v[108:111], v[124:127]
	ds_read_b128 v[96:99], v191 offset:36864
	ds_read_b128 v[100:103], v192 offset:36864
	ds_read_b128 v[104:107], v191 offset:38912
	ds_read_b128 v[108:111], v192 offset:38912
	s_waitcnt vmcnt(6)
	s_waitcnt lgkmcnt(0)
	v_mfma_f32_16x16x32_bf16 v[208:211], v[64:67], v[96:99], 0
	v_sub_f32_e32 v112, v112, v224
	v_sub_f32_e32 v113, v113, v225
	v_sub_f32_e32 v114, v114, v226
	v_sub_f32_e32 v115, v115, v227
	v_sub_f32_e32 v116, v116, v228
	v_sub_f32_e32 v117, v117, v229
	v_sub_f32_e32 v118, v118, v230
	v_sub_f32_e32 v119, v119, v231
	v_sub_f32_e32 v120, v120, v224
	v_sub_f32_e32 v121, v121, v225
	v_sub_f32_e32 v122, v122, v226
	v_sub_f32_e32 v123, v123, v227
	v_mfma_f32_16x16x32_bf16 v[212:215], v[68:71], v[96:99], 0
	v_sub_f32_e32 v124, v124, v228
	v_sub_f32_e32 v125, v125, v229
	v_sub_f32_e32 v126, v126, v230
	v_sub_f32_e32 v127, v127, v231
	v_max3_f32 v240, v112, v113, v114
	v_max3_f32 v240, v240, v115, v116
	v_max3_f32 v240, v240, v117, v118
	v_max_f32_e32 v240, v240, v119
	v_max3_f32 v241, v120, v121, v122
	v_max3_f32 v241, v241, v123, v124
	v_max3_f32 v241, v241, v125, v126
	v_max_f32_e32 v241, v241, v127
	v_mfma_f32_16x16x32_bf16 v[216:219], v[64:67], v[104:107], 0
	v_add_f32_e32 v240, v240, v131
	v_add_f32_e32 v241, v241, v155
	v_mov_b32_e32 v242, v240
	v_mov_b32_e32 v243, v241
	s_nop 1
	v_permlane16_swap_b32_e32 v240, v242
	v_permlane16_swap_b32_e32 v241, v243
	v_max_f32_e32 v240, v240, v242
	v_max_f32_e32 v241, v241, v243
	v_mov_b32_e32 v242, v240
	v_mov_b32_e32 v243, v241
	s_nop 1
	v_permlane32_swap_b32_e32 v240, v242
	v_permlane32_swap_b32_e32 v241, v243
	v_max3_f32 v240, v186, v240, v242
	v_sub_f32_e32 v244, v186, v240
	v_sub_f32_e32 v246, v240, v131
	v_exp_f32_e32 v244, v244
	v_mov_b32_e32 v186, v240
	v_max3_f32 v241, v185, v241, v243
	v_sub_f32_e32 v245, v185, v241
	v_sub_f32_e32 v247, v241, v155
	v_exp_f32_e32 v245, v245
	v_mov_b32_e32 v185, v241
	v_mfma_f32_16x16x32_bf16 v[220:223], v[68:71], v[104:107], 0
	v_sub_f32_e32 v112, v112, v246
	v_sub_f32_e32 v113, v113, v246
	v_sub_f32_e32 v114, v114, v246
	v_sub_f32_e32 v115, v115, v246
	v_sub_f32_e32 v116, v116, v246
	v_sub_f32_e32 v117, v117, v246
	v_sub_f32_e32 v118, v118, v246
	v_sub_f32_e32 v119, v119, v246
	v_sub_f32_e32 v120, v120, v247
	v_sub_f32_e32 v121, v121, v247
	v_sub_f32_e32 v122, v122, v247
	v_mfma_f32_16x16x32_bf16 v[208:211], v[72:75], v[100:103], v[208:211]
	v_sub_f32_e32 v123, v123, v247
	v_sub_f32_e32 v124, v124, v247
	v_sub_f32_e32 v125, v125, v247
	v_sub_f32_e32 v126, v126, v247
	v_sub_f32_e32 v127, v127, v247
	v_exp_f32_e32 v112, v112
	v_exp_f32_e32 v113, v113
	v_exp_f32_e32 v114, v114
	v_exp_f32_e32 v115, v115
	v_exp_f32_e32 v116, v116
	v_exp_f32_e32 v117, v117
	v_exp_f32_e32 v118, v118
	v_mfma_f32_16x16x32_bf16 v[212:215], v[76:79], v[100:103], v[212:215]
	v_exp_f32_e32 v119, v119
	v_exp_f32_e32 v120, v120
	v_exp_f32_e32 v121, v121
	v_exp_f32_e32 v122, v122
	v_exp_f32_e32 v123, v123
	v_exp_f32_e32 v124, v124
	v_exp_f32_e32 v125, v125
	v_exp_f32_e32 v126, v126
	v_exp_f32_e32 v127, v127
	v_add_f32_e32 v240, v112, v113
	v_add_f32_e32 v242, v114, v115
	v_add_f32_e32 v240, v240, v242
	v_mfma_f32_16x16x32_bf16 v[216:219], v[72:75], v[108:111], v[216:219]
	v_add_f32_e32 v242, v116, v117
	v_add_f32_e32 v240, v240, v242
	v_add_f32_e32 v242, v118, v119
	v_add_f32_e32 v240, v240, v242
	v_fma_f32 v157, v157, v244, v240
	v_add_f32_e32 v241, v120, v121
	v_add_f32_e32 v243, v122, v123
	v_add_f32_e32 v241, v241, v243
	v_add_f32_e32 v243, v124, v125
	v_add_f32_e32 v241, v241, v243
	v_add_f32_e32 v243, v126, v127
	v_add_f32_e32 v241, v241, v243
	v_mfma_f32_16x16x32_bf16 v[220:223], v[76:79], v[108:111], v[220:223]
	ds_read_b128 v[64:67], v248 offset:4096
	ds_read_b128 v[68:71], v248 offset:6144
	ds_read_b128 v[72:75], v249 offset:4096
	ds_read_b128 v[76:79], v249 offset:6144
	ds_read_b128 v[96:99], v191 offset:32768
	ds_read_b128 v[100:103], v192 offset:32768
	ds_read_b128 v[104:107], v191 offset:34816
	ds_read_b128 v[108:111], v192 offset:34816
	v_fma_f32 v156, v156, v245, v241
	v_cvt_pk_bf16_f32 v112, v112, v113
	v_cvt_pk_bf16_f32 v113, v114, v115
	v_cvt_pk_bf16_f32 v114, v116, v117
	v_cvt_pk_bf16_f32 v115, v118, v119
	v_cvt_pk_bf16_f32 v120, v120, v121
	v_cvt_pk_bf16_f32 v121, v122, v123
	v_cvt_pk_bf16_f32 v122, v124, v125
	v_cvt_pk_bf16_f32 v123, v126, v127
	v_cmp_neq_f32_e32 vcc, 1.0, v244
	s_nop 1
	s_cbranch_vccz .Lfoxf_r0
	v_mul_f32_e32 v60, v60, v244
	v_mul_f32_e32 v61, v61, v244
	v_mul_f32_e32 v62, v62, v244
	v_mul_f32_e32 v63, v63, v244
	v_mul_f32_e32 v56, v56, v244
	v_mul_f32_e32 v57, v57, v244
	v_mul_f32_e32 v58, v58, v244
	v_mul_f32_e32 v59, v59, v244
	v_mul_f32_e32 v52, v52, v244
	v_mul_f32_e32 v53, v53, v244
	v_mul_f32_e32 v54, v54, v244
	v_mul_f32_e32 v55, v55, v244
	v_mul_f32_e32 v48, v48, v244
	v_mul_f32_e32 v49, v49, v244
	v_mul_f32_e32 v50, v50, v244
	v_mul_f32_e32 v51, v51, v244

.Lfoxf_r3:
	s_waitcnt vmcnt(4)
	v_mfma_f32_16x16x32_bf16 v[40:43], v[80:83], v[208:211], v[40:43]
	v_sub_f32_e32 v112, v112, v232
	v_sub_f32_e32 v113, v113, v233
	v_sub_f32_e32 v114, v114, v234
	v_sub_f32_e32 v115, v115, v235
	v_sub_f32_e32 v116, v116, v236
	v_sub_f32_e32 v117, v117, v237
	v_mfma_f32_16x16x32_bf16 v[12:15], v[80:83], v[216:219], v[12:15]
	v_sub_f32_e32 v118, v118, v238
	v_sub_f32_e32 v119, v119, v239
	v_sub_f32_e32 v120, v120, v232
	v_sub_f32_e32 v121, v121, v233
	v_sub_f32_e32 v122, v122, v234
	v_sub_f32_e32 v123, v123, v235
	v_mfma_f32_16x16x32_bf16 v[24:27], v[84:87], v[208:211], v[24:27]
	v_sub_f32_e32 v124, v124, v236
	v_sub_f32_e32 v125, v125, v237
	v_sub_f32_e32 v126, v126, v238
	v_sub_f32_e32 v127, v127, v239
	v_max3_f32 v240, v112, v113, v114
	v_max3_f32 v240, v240, v115, v116
	v_mfma_f32_16x16x32_bf16 v[8:11], v[84:87], v[216:219], v[8:11]
	v_max3_f32 v240, v240, v117, v118
	v_max_f32_e32 v240, v240, v119
	v_max3_f32 v241, v120, v121, v122
	v_max3_f32 v241, v241, v123, v124
	v_max3_f32 v241, v241, v125, v126
	v_max_f32_e32 v241, v241, v127
	v_mfma_f32_16x16x32_bf16 v[20:23], v[88:91], v[208:211], v[20:23]
	v_add_f32_e32 v240, v240, v131
	v_add_f32_e32 v241, v241, v155
	v_mov_b32_e32 v242, v240
	v_mov_b32_e32 v243, v241
	s_nop 1
	v_permlane16_swap_b32_e32 v240, v242
	v_permlane16_swap_b32_e32 v241, v243
	v_max_f32_e32 v240, v240, v242
	v_max_f32_e32 v241, v241, v243
	v_mov_b32_e32 v242, v240
	v_mov_b32_e32 v243, v241
	s_nop 1
	v_permlane32_swap_b32_e32 v240, v242
	v_permlane32_swap_b32_e32 v241, v243
	v_max3_f32 v240, v186, v240, v242
	v_sub_f32_e32 v244, v186, v240
	v_sub_f32_e32 v246, v240, v131
	v_exp_f32_e32 v244, v244
	v_mfma_f32_16x16x32_bf16 v[0:3], v[88:91], v[216:219], v[0:3]
	v_mov_b32_e32 v186, v240
	v_max3_f32 v241, v185, v241, v243
	v_sub_f32_e32 v245, v185, v241
	v_sub_f32_e32 v247, v241, v155
	v_exp_f32_e32 v245, v245
	v_mov_b32_e32 v185, v241
	v_mfma_f32_16x16x32_bf16 v[16:19], v[92:95], v[208:211], v[16:19]
	v_sub_f32_e32 v112, v112, v246
	v_sub_f32_e32 v113, v113, v246
	v_sub_f32_e32 v114, v114, v246
	v_sub_f32_e32 v115, v115, v246
	v_sub_f32_e32 v116, v116, v246
	v_sub_f32_e32 v117, v117, v246
	v_mfma_f32_16x16x32_bf16 v[4:7], v[92:95], v[216:219], v[4:7]
	v_sub_f32_e32 v118, v118, v246
	v_sub_f32_e32 v119, v119, v246
	v_sub_f32_e32 v120, v120, v247
	v_sub_f32_e32 v121, v121, v247
	v_sub_f32_e32 v122, v122, v247
	ds_read_b64 v[80:81], v189 offset:8192
	ds_read_b64 v[82:83], v190 offset:8192
	ds_read_b64 v[84:85], v189 offset:10240
	ds_read_b64 v[86:87], v190 offset:10240
	ds_read_b64 v[88:89], v189 offset:12288
	ds_read_b64 v[90:91], v190 offset:12288
	ds_read_b64 v[92:93], v189 offset:14336
	ds_read_b64 v[94:95], v190 offset:14336
	s_waitcnt lgkmcnt(8)
	v_mfma_f32_16x16x32_bf16 v[208:211], v[64:67], v[96:99], 0
	v_sub_f32_e32 v123, v123, v247
	v_sub_f32_e32 v124, v124, v247
	v_sub_f32_e32 v125, v125, v247
	v_sub_f32_e32 v126, v126, v247
	v_sub_f32_e32 v127, v127, v247
	v_exp_f32_e32 v112, v112
	v_mfma_f32_16x16x32_bf16 v[212:215], v[68:71], v[96:99], 0
	v_exp_f32_e32 v113, v113
	v_exp_f32_e32 v114, v114
	v_exp_f32_e32 v115, v115
	v_exp_f32_e32 v116, v116
	v_exp_f32_e32 v117, v117
	v_exp_f32_e32 v118, v118
	v_mfma_f32_16x16x32_bf16 v[216:219], v[64:67], v[104:107], 0
	v_exp_f32_e32 v119, v119
	v_exp_f32_e32 v120, v120
	v_exp_f32_e32 v121, v121
	v_exp_f32_e32 v122, v122
	v_exp_f32_e32 v123, v123
	v_exp_f32_e32 v124, v124
	v_mfma_f32_16x16x32_bf16 v[220:223], v[68:71], v[104:107], 0
	v_exp_f32_e32 v125, v125
	v_exp_f32_e32 v126, v126
	v_exp_f32_e32 v127, v127
	v_add_f32_e32 v240, v112, v113
	v_add_f32_e32 v242, v114, v115
	v_add_f32_e32 v240, v240, v242
	v_mfma_f32_16x16x32_bf16 v[208:211], v[72:75], v[100:103], v[208:211]
	v_add_f32_e32 v242, v116, v117
	v_add_f32_e32 v240, v240, v242
	v_add_f32_e32 v242, v118, v119
	v_add_f32_e32 v240, v240, v242
	v_fma_f32 v157, v157, v244, v240
	v_add_f32_e32 v241, v120, v121
	v_mfma_f32_16x16x32_bf16 v[212:215], v[76:79], v[100:103], v[212:215]
	v_add_f32_e32 v243, v122, v123
	v_add_f32_e32 v241, v241, v243
	v_add_f32_e32 v243, v124, v125
	v_add_f32_e32 v241, v241, v243
	v_add_f32_e32 v243, v126, v127
	v_add_f32_e32 v241, v241, v243
	v_mfma_f32_16x16x32_bf16 v[216:219], v[72:75], v[108:111], v[216:219]
	v_fma_f32 v156, v156, v245, v241
	v_cvt_pk_bf16_f32 v112, v112, v113
	v_cvt_pk_bf16_f32 v113, v114, v115
	v_cvt_pk_bf16_f32 v114, v116, v117
	v_cvt_pk_bf16_f32 v115, v118, v119
	v_cvt_pk_bf16_f32 v120, v120, v121
	v_mfma_f32_16x16x32_bf16 v[220:223], v[76:79], v[108:111], v[220:223]
	v_cvt_pk_bf16_f32 v121, v122, v123
	v_cvt_pk_bf16_f32 v122, v124, v125
	v_cvt_pk_bf16_f32 v123, v126, v127
	v_cmp_neq_f32_e32 vcc, 1.0, v244
	s_nop 1
	s_cbranch_vccz .Lfoxf_r4
	v_mul_f32_e32 v60, v60, v244
	v_mul_f32_e32 v61, v61, v244
	v_mul_f32_e32 v62, v62, v244
	v_mul_f32_e32 v63, v63, v244
	v_mul_f32_e32 v56, v56, v244
	v_mul_f32_e32 v57, v57, v244
	v_mul_f32_e32 v58, v58, v244
	v_mul_f32_e32 v59, v59, v244
	v_mul_f32_e32 v52, v52, v244
	v_mul_f32_e32 v53, v53, v244
	v_mul_f32_e32 v54, v54, v244
	v_mul_f32_e32 v55, v55, v244
	v_mul_f32_e32 v48, v48, v244
	v_mul_f32_e32 v49, v49, v244
	v_mul_f32_e32 v50, v50, v244
	v_mul_f32_e32 v51, v51, v244
